# QKV epilogue: rope-table loads software-pipelined one row-group ahead into two alternating free register sets, store-ack waits dropped (on top of pipelined norm loop)
# speedup vs baseline: 1.0016x; 1.0016x over previous
; __device__ __forceinline__ unsigned cvt_pk_bf16(float lo, float hi) { const cvt_f32x2 v = {lo, hi}; return __builtin_bit_cast(unsigned, __builtin_convertvector(v, cvt_bf16x2)); }
;     __device__ __forceinline__ void operator()(const f32x4 (&acc)[2][2][4][2], const Unit& u, int wr, int wc, int fr, int fq) const {
;     ...
;                 const int row = u.pm * BM + ai * HALF + wr * 64 + m * 16 + fr;
;                 f32x4 a0 = acc[ai][0][m][0], a1 = acc[ai][0][m][1], b0 = acc[ai][1][m][0], b1 = acc[ai][1][m][1];
;                 if (do_norm) {
;                     float ss = 0.f;
; #pragma unroll
;                     for (int e = 0; e < 4; ++e) ss += a0[e] * a0[e] + a1[e] * a1[e] + b0[e] * b0[e] + b1[e] * b1[e];
;                     ss += __shfl_xor(ss, 16); ss += __shfl_xor(ss, 32);
;                     const float r = __builtin_amdgcn_rsqf(ss * (1.0f / 64.0f) + 1e-6f);
;                     a0 = a0 * r * ga[0]; a1 = a1 * r * ga[1]; b0 = b0 * r * gb[0]; b1 = b1 * r * gb[1];
;                 }
;                 if (do_rope) {
;                     const int s = row & 4095, pos = half ? (s & 63) : (s >> 6);
;                     const f32x4 c0 = *(const f32x4*)(rope + pos * 32 + jb), c1 = *(const f32x4*)(rope + pos * 32 + jb + 4);
;                     const f32x4 s0 = *(const f32x4*)(rope + pos * 32 + 16 + jb), s1 = *(const f32x4*)(rope + pos * 32 + 16 + jb + 4);
;                     const f32x4 x0 = a0, x1 = a1, y0 = b0, y1 = b1;
;                     a0 = x0 * c0 - y0 * s0; b0 = y0 * c0 + x0 * s0; a1 = x1 * c1 - y1 * s1; b1 = y1 * c1 + x1 * s1;
;                 }
;                 a0 = a0 * qs; a1 = a1 * qs; b0 = b0 * qs; b1 = b1 * qs;
;                 bf16_t* rowp = O + (size_t)row * ldc + hs * 64 + D0;
;                 u32x4 w;
;                 w.x = cvt_pk_bf16(a0[0], a0[1]); w.y = cvt_pk_bf16(a0[2], a0[3]); w.z = cvt_pk_bf16(a1[0], a1[1]); w.w = cvt_pk_bf16(a1[2], a1[3]); *(u32x4*)(rowp) = w;
;                 w.x = cvt_pk_bf16(b0[0], b0[1]); w.y = cvt_pk_bf16(b0[2], b0[3]); w.z = cvt_pk_bf16(b1[0], b1[1]); w.w = cvt_pk_bf16(b1[2], b1[3]); *(u32x4*)(rowp + 16) = w;
.LBB0_55:
	s_lshl_b32 s3, s2, 8
	s_add_i32 s3, s3, s53
	s_bfe_u32 s23, s3, 0x60006
	s_and_b64 s[4:5], s[36:37], s[4:5]
	s_cmpk_lt_i32 s2, 0x80
	s_cselect_b64 s[12:13], -1, 0
	s_and_b64 s[4:5], s[4:5], s[12:13]
	v_cndmask_b32_e64 v160, 0, 1, s[4:5]
	v_cmp_ne_u32_e64 s[12:13], 1, v160
	s_andn2_b64 vcc, exec, s[4:5]
	s_cbranch_vccnz .LBB0_57
	v_mov_b32_e32 v232, s23
	v_cndmask_b32_e64 v232, v153, v232, s[6:7]
	v_lshlrev_b32_e32 v232, 7, v232
	v_mov_b32_e32 v233, v193
	v_lshl_add_u64 v[232:233], v[154:155], 0, v[232:233]
	global_load_dwordx4 v[200:203], v[232:233], off offset:16
	global_load_dwordx4 v[204:207], v[232:233], off
	global_load_dwordx4 v[208:211], v[232:233], off offset:80
	global_load_dwordx4 v[212:215], v[232:233], off offset:64
	s_waitcnt vmcnt(0)
	v_pk_mul_f32 v[186:187], v[132:133], v[212:213]
	v_pk_mul_f32 v[160:161], v[134:135], v[214:215]
	v_pk_fma_f32 v[186:187], v[140:141], v[204:205], v[186:187] neg_lo:[0,0,1] neg_hi:[0,0,1]
	v_pk_mul_f32 v[140:141], v[140:141], v[212:213]
	v_pk_fma_f32 v[188:189], v[142:143], v[206:207], v[160:161] neg_lo:[0,0,1] neg_hi:[0,0,1]
	v_pk_mul_f32 v[142:143], v[142:143], v[214:215]
	v_pk_fma_f32 v[132:133], v[132:133], v[204:205], v[140:141]
	v_pk_mul_f32 v[140:141], v[130:131], v[210:211]
	v_pk_mul_f32 v[160:161], v[128:129], v[208:209]
	v_pk_fma_f32 v[134:135], v[134:135], v[206:207], v[142:143]
	v_pk_fma_f32 v[142:143], v[138:139], v[202:203], v[140:141] neg_lo:[0,0,1] neg_hi:[0,0,1]
	v_pk_fma_f32 v[140:141], v[136:137], v[200:201], v[160:161] neg_lo:[0,0,1] neg_hi:[0,0,1]
	v_pk_mul_f32 v[138:139], v[138:139], v[210:211]
	v_pk_mul_f32 v[136:137], v[136:137], v[208:209]
	v_pk_fma_f32 v[130:131], v[130:131], v[202:203], v[138:139]
	v_pk_fma_f32 v[128:129], v[128:129], v[200:201], v[136:137]
	v_mov_b64_e32 v[136:137], v[140:141]
	v_mov_b64_e32 v[138:139], v[142:143]
	v_mov_b64_e32 v[140:141], v[186:187]
	v_mov_b64_e32 v[142:143], v[188:189]
	v_mov_b32_e32 v232, s23
	v_cndmask_b32_e64 v232, v163, v232, s[6:7]
	v_lshlrev_b32_e32 v232, 7, v232
	v_mov_b32_e32 v233, v193
	v_lshl_add_u64 v[232:233], v[154:155], 0, v[232:233]
	global_load_dwordx4 v[234:237], v[232:233], off offset:16
	global_load_dwordx4 v[238:241], v[232:233], off
	global_load_dwordx4 v[242:245], v[232:233], off offset:80
	global_load_dwordx4 v[248:251], v[232:233], off offset:64
.LBB0_57:
	v_cndmask_b32_e64 v160, 1.0, v253, s[14:15]
	v_or_b32_e32 v161, s3, v153
	s_lshl_b32 s14, s25, 6
	v_pk_mul_f32 v[172:173], v[160:161], v[128:129] op_sel_hi:[0,1]
	v_mad_i64_i32 v[128:129], s[4:5], v161, s38, 0
	s_ashr_i32 s15, s14, 31
	v_lshl_add_u64 v[128:129], v[128:129], 1, s[58:59]
	v_pk_mul_f32 v[142:143], v[160:161], v[142:143] op_sel_hi:[0,1]
	v_pk_mul_f32 v[140:141], v[160:161], v[140:141] op_sel_hi:[0,1]
	v_pk_mul_f32 v[138:139], v[160:161], v[138:139] op_sel_hi:[0,1]
	v_pk_mul_f32 v[136:137], v[160:161], v[136:137] op_sel_hi:[0,1]
	v_lshl_add_u64 v[128:129], s[14:15], 1, v[128:129]
	v_pk_mul_f32 v[134:135], v[160:161], v[134:135] op_sel_hi:[0,1]
	v_pk_mul_f32 v[132:133], v[160:161], v[132:133] op_sel_hi:[0,1]
	v_pk_mul_f32 v[170:171], v[160:161], v[130:131] op_sel_hi:[0,1]
	v_lshl_add_u64 v[174:175], v[128:129], 0, v[192:193]
	v_cvt_pk_bf16_f32 v128, v140, v141
	v_cvt_pk_bf16_f32 v129, v142, v143
	v_cvt_pk_bf16_f32 v130, v136, v137
	v_cvt_pk_bf16_f32 v131, v138, v139
	global_store_dwordx4 v[174:175], v[128:131], off
	s_and_b64 vcc, exec, s[10:11]
	s_nop 0
	v_cvt_pk_bf16_f32 v128, v132, v133
	v_cvt_pk_bf16_f32 v129, v134, v135
	v_cvt_pk_bf16_f32 v130, v172, v173
	v_cvt_pk_bf16_f32 v131, v170, v171
	global_store_dwordx4 v[174:175], v[128:131], off offset:32
	s_cbranch_vccnz .LBB0_59
	s_nop 0
	v_pk_mul_f32 v[130:131], v[120:121], v[120:121]
	v_pk_mul_f32 v[128:129], v[122:123], v[122:123]
	v_pk_fma_f32 v[130:131], v[124:125], v[124:125], v[130:131]
	v_pk_fma_f32 v[128:129], v[126:127], v[126:127], v[128:129]
	v_pk_fma_f32 v[130:131], v[116:117], v[116:117], v[130:131]
	v_pk_fma_f32 v[128:129], v[118:119], v[118:119], v[128:129]
	v_pk_fma_f32 v[130:131], v[112:113], v[112:113], v[130:131]
	v_pk_fma_f32 v[128:129], v[114:115], v[114:115], v[128:129]
	v_add_f32_e32 v130, v130, v131
	v_add_f32_e32 v128, v128, v130
	v_add_f32_e32 v128, v129, v128
	ds_bpermute_b32 v129, v166, v128
	s_waitcnt lgkmcnt(0)
	v_add_f32_e32 v128, v128, v129
	ds_bpermute_b32 v129, v167, v128
	s_waitcnt lgkmcnt(0)
	v_add_f32_e32 v128, v128, v129
	v_fmamk_f32 v128, v128, 0x3c800000, v224
	v_rsq_f32_e32 v128, v128
	s_nop 0
	v_pk_mul_f32 v[124:125], v[124:125], v[128:129] op_sel_hi:[1,0]
	v_pk_mul_f32 v[126:127], v[126:127], v[128:129] op_sel_hi:[1,0]
	v_pk_mul_f32 v[120:121], v[120:121], v[128:129] op_sel_hi:[1,0]
	v_pk_mul_f32 v[122:123], v[122:123], v[128:129] op_sel_hi:[1,0]
	v_pk_mul_f32 v[116:117], v[116:117], v[128:129] op_sel_hi:[1,0]
	v_pk_mul_f32 v[118:119], v[118:119], v[128:129] op_sel_hi:[1,0]
	v_pk_mul_f32 v[112:113], v[112:113], v[128:129] op_sel_hi:[1,0]
	v_pk_mul_f32 v[114:115], v[114:115], v[128:129] op_sel_hi:[1,0]
	v_pk_mul_f32 v[126:127], v[70:71], v[126:127]
	v_pk_mul_f32 v[124:125], v[68:69], v[124:125]
	v_pk_mul_f32 v[122:123], v[78:79], v[122:123]
	v_pk_mul_f32 v[120:121], v[76:77], v[120:121]
	v_pk_mul_f32 v[118:119], v[58:59], v[118:119]
	v_pk_mul_f32 v[116:117], v[56:57], v[116:117]
	v_pk_mul_f32 v[114:115], v[66:67], v[114:115]
	v_pk_mul_f32 v[112:113], v[64:65], v[112:113]
; __device__ __forceinline__ unsigned cvt_pk_bf16(float lo, float hi) { const cvt_f32x2 v = {lo, hi}; return __builtin_bit_cast(unsigned, __builtin_convertvector(v, cvt_bf16x2)); }
;     __device__ __forceinline__ void operator()(const f32x4 (&acc)[2][2][4][2], const Unit& u, int wr, int wc, int fr, int fq) const {
;     ...
;                 if (do_norm) {
;                     float ss = 0.f;
; #pragma unroll
;                     for (int e = 0; e < 4; ++e) ss += a0[e] * a0[e] + a1[e] * a1[e] + b0[e] * b0[e] + b1[e] * b1[e];
;                     ss += __shfl_xor(ss, 16); ss += __shfl_xor(ss, 32);
;                     const float r = __builtin_amdgcn_rsqf(ss * (1.0f / 64.0f) + 1e-6f);
;                     a0 = a0 * r * ga[0]; a1 = a1 * r * ga[1]; b0 = b0 * r * gb[0]; b1 = b1 * r * gb[1];
;                 }
;                 if (do_rope) {
;                     const int s = row & 4095, pos = half ? (s & 63) : (s >> 6);
;                     const f32x4 c0 = *(const f32x4*)(rope + pos * 32 + jb), c1 = *(const f32x4*)(rope + pos * 32 + jb + 4);
;                     const f32x4 s0 = *(const f32x4*)(rope + pos * 32 + 16 + jb), s1 = *(const f32x4*)(rope + pos * 32 + 16 + jb + 4);
;                     const f32x4 x0 = a0, x1 = a1, y0 = b0, y1 = b1;
;                     a0 = x0 * c0 - y0 * s0; b0 = y0 * c0 + x0 * s0; a1 = x1 * c1 - y1 * s1; b1 = y1 * c1 + x1 * s1;
;                 }
;                 a0 = a0 * qs; a1 = a1 * qs; b0 = b0 * qs; b1 = b1 * qs;
;                 bf16_t* rowp = O + (size_t)row * ldc + hs * 64 + D0;
;                 u32x4 w;
;                 w.x = cvt_pk_bf16(a0[0], a0[1]); w.y = cvt_pk_bf16(a0[2], a0[3]); w.z = cvt_pk_bf16(a1[0], a1[1]); w.w = cvt_pk_bf16(a1[2], a1[3]); *(u32x4*)(rowp) = w;
;                 w.x = cvt_pk_bf16(b0[0], b0[1]); w.y = cvt_pk_bf16(b0[2], b0[3]); w.z = cvt_pk_bf16(b1[0], b1[1]); w.w = cvt_pk_bf16(b1[2], b1[3]); *(u32x4*)(rowp + 16) = w;
.LBB0_59:
	s_and_b64 vcc, exec, s[12:13]
	s_cbranch_vccnz .LBB0_61
	s_waitcnt vmcnt(2)
	v_pk_mul_f32 v[170:171], v[118:119], v[250:251]
	v_pk_mul_f32 v[174:175], v[116:117], v[248:249]
	v_pk_fma_f32 v[172:173], v[126:127], v[240:241], v[170:171] neg_lo:[0,0,1] neg_hi:[0,0,1]
	v_pk_fma_f32 v[170:171], v[124:125], v[238:239], v[174:175] neg_lo:[0,0,1] neg_hi:[0,0,1]
	v_pk_mul_f32 v[124:125], v[124:125], v[248:249]
	v_pk_mul_f32 v[126:127], v[126:127], v[250:251]
	v_pk_fma_f32 v[116:117], v[116:117], v[238:239], v[124:125]
	v_pk_mul_f32 v[124:125], v[114:115], v[244:245]
	v_pk_mul_f32 v[238:239], v[112:113], v[242:243]
	v_pk_fma_f32 v[118:119], v[118:119], v[240:241], v[126:127]
	v_pk_fma_f32 v[126:127], v[122:123], v[236:237], v[124:125] neg_lo:[0,0,1] neg_hi:[0,0,1]
	v_pk_fma_f32 v[124:125], v[120:121], v[234:235], v[238:239] neg_lo:[0,0,1] neg_hi:[0,0,1]
	v_pk_mul_f32 v[122:123], v[122:123], v[244:245]
	v_pk_mul_f32 v[120:121], v[120:121], v[242:243]
	v_pk_fma_f32 v[114:115], v[114:115], v[236:237], v[122:123]
	v_pk_fma_f32 v[112:113], v[112:113], v[234:235], v[120:121]
	v_mov_b64_e32 v[120:121], v[124:125]
	v_mov_b64_e32 v[122:123], v[126:127]
	v_mov_b64_e32 v[124:125], v[170:171]
	v_mov_b64_e32 v[126:127], v[172:173]
	v_mov_b32_e32 v232, s23
	v_cndmask_b32_e64 v232, v164, v232, s[6:7]
	v_lshlrev_b32_e32 v232, 7, v232
	v_mov_b32_e32 v233, v193
	v_lshl_add_u64 v[232:233], v[154:155], 0, v[232:233]
	global_load_dwordx4 v[200:203], v[232:233], off offset:16
	global_load_dwordx4 v[204:207], v[232:233], off
	global_load_dwordx4 v[208:211], v[232:233], off offset:80
	global_load_dwordx4 v[212:215], v[232:233], off offset:64
.LBB0_61:
	v_mov_b32_e32 v161, v160
	v_or_b32_e32 v132, s3, v163
	v_pk_mul_f32 v[130:131], v[160:161], v[112:113]
	v_mad_i64_i32 v[112:113], s[4:5], v132, s38, 0
	v_mov_b32_e32 v128, v160
	v_mov_b32_e32 v129, v160
	v_lshl_add_u64 v[112:113], v[112:113], 1, s[58:59]
	v_pk_mul_f32 v[126:127], v[128:129], v[126:127]
	v_pk_mul_f32 v[124:125], v[160:161], v[124:125]
	v_pk_mul_f32 v[122:123], v[128:129], v[122:123]
	v_pk_mul_f32 v[120:121], v[160:161], v[120:121]
	v_lshl_add_u64 v[112:113], s[14:15], 1, v[112:113]
	v_pk_mul_f32 v[118:119], v[128:129], v[118:119]
	v_pk_mul_f32 v[116:117], v[160:161], v[116:117]
	v_pk_mul_f32 v[128:129], v[128:129], v[114:115]
	v_lshl_add_u64 v[132:133], v[112:113], 0, v[192:193]
	v_cvt_pk_bf16_f32 v112, v124, v125
	v_cvt_pk_bf16_f32 v113, v126, v127
	v_cvt_pk_bf16_f32 v114, v120, v121
	v_cvt_pk_bf16_f32 v115, v122, v123
	global_store_dwordx4 v[132:133], v[112:115], off
	s_and_b64 vcc, exec, s[10:11]
	s_nop 0
	v_cvt_pk_bf16_f32 v112, v116, v117
	v_cvt_pk_bf16_f32 v113, v118, v119
	v_cvt_pk_bf16_f32 v114, v130, v131
	v_cvt_pk_bf16_f32 v115, v128, v129
	global_store_dwordx4 v[132:133], v[112:115], off offset:32
	s_cbranch_vccnz .LBB0_63
	s_nop 0
	v_pk_mul_f32 v[114:115], v[104:105], v[104:105]
	v_pk_mul_f32 v[112:113], v[106:107], v[106:107]
	v_pk_fma_f32 v[114:115], v[108:109], v[108:109], v[114:115]
	v_pk_fma_f32 v[112:113], v[110:111], v[110:111], v[112:113]
	v_pk_fma_f32 v[114:115], v[100:101], v[100:101], v[114:115]
	v_pk_fma_f32 v[112:113], v[102:103], v[102:103], v[112:113]
	v_pk_fma_f32 v[114:115], v[96:97], v[96:97], v[114:115]
	v_pk_fma_f32 v[112:113], v[98:99], v[98:99], v[112:113]
	v_add_f32_e32 v114, v114, v115
	v_add_f32_e32 v112, v112, v114
	v_add_f32_e32 v112, v113, v112
	ds_bpermute_b32 v113, v166, v112
	s_waitcnt lgkmcnt(0)
	v_add_f32_e32 v112, v112, v113
	ds_bpermute_b32 v113, v167, v112
	s_waitcnt lgkmcnt(0)
	v_add_f32_e32 v112, v112, v113
	v_fmamk_f32 v112, v112, 0x3c800000, v224
	v_rsq_f32_e32 v112, v112
	s_nop 0
	v_pk_mul_f32 v[108:109], v[108:109], v[112:113] op_sel_hi:[1,0]
	v_pk_mul_f32 v[110:111], v[110:111], v[112:113] op_sel_hi:[1,0]
	v_pk_mul_f32 v[104:105], v[104:105], v[112:113] op_sel_hi:[1,0]
	v_pk_mul_f32 v[106:107], v[106:107], v[112:113] op_sel_hi:[1,0]
	v_pk_mul_f32 v[100:101], v[100:101], v[112:113] op_sel_hi:[1,0]
	v_pk_mul_f32 v[102:103], v[102:103], v[112:113] op_sel_hi:[1,0]
	v_pk_mul_f32 v[96:97], v[96:97], v[112:113] op_sel_hi:[1,0]
	v_pk_mul_f32 v[98:99], v[98:99], v[112:113] op_sel_hi:[1,0]
	v_pk_mul_f32 v[110:111], v[70:71], v[110:111]
	v_pk_mul_f32 v[108:109], v[68:69], v[108:109]
	v_pk_mul_f32 v[106:107], v[78:79], v[106:107]
	v_pk_mul_f32 v[104:105], v[76:77], v[104:105]
	v_pk_mul_f32 v[102:103], v[58:59], v[102:103]
	v_pk_mul_f32 v[100:101], v[56:57], v[100:101]
	v_pk_mul_f32 v[98:99], v[66:67], v[98:99]
	v_pk_mul_f32 v[96:97], v[64:65], v[96:97]
.LBB0_63:
	s_and_b64 vcc, exec, s[12:13]
	s_cbranch_vccnz .LBB0_65
	s_waitcnt vmcnt(2)
	v_pk_mul_f32 v[128:129], v[102:103], v[214:215]
	v_pk_mul_f32 v[132:133], v[100:101], v[212:213]
	v_pk_fma_f32 v[130:131], v[110:111], v[206:207], v[128:129] neg_lo:[0,0,1] neg_hi:[0,0,1]
	v_pk_fma_f32 v[128:129], v[108:109], v[204:205], v[132:133] neg_lo:[0,0,1] neg_hi:[0,0,1]
	v_pk_mul_f32 v[108:109], v[108:109], v[212:213]
	v_pk_mul_f32 v[110:111], v[110:111], v[214:215]
	v_pk_fma_f32 v[100:101], v[100:101], v[204:205], v[108:109]
	v_pk_mul_f32 v[108:109], v[98:99], v[210:211]
	v_pk_mul_f32 v[204:205], v[96:97], v[208:209]
	v_pk_fma_f32 v[102:103], v[102:103], v[206:207], v[110:111]
	v_pk_fma_f32 v[110:111], v[106:107], v[202:203], v[108:109] neg_lo:[0,0,1] neg_hi:[0,0,1]
	v_pk_fma_f32 v[108:109], v[104:105], v[200:201], v[204:205] neg_lo:[0,0,1] neg_hi:[0,0,1]
	v_pk_mul_f32 v[106:107], v[106:107], v[210:211]
	v_pk_mul_f32 v[104:105], v[104:105], v[208:209]
	v_pk_fma_f32 v[98:99], v[98:99], v[202:203], v[106:107]
	v_pk_fma_f32 v[96:97], v[96:97], v[200:201], v[104:105]
	v_mov_b64_e32 v[104:105], v[108:109]
	v_mov_b64_e32 v[106:107], v[110:111]
	v_mov_b64_e32 v[108:109], v[128:129]
	v_mov_b64_e32 v[110:111], v[130:131]
	v_mov_b32_e32 v232, s23
	v_cndmask_b32_e64 v232, v165, v232, s[6:7]
	v_lshlrev_b32_e32 v232, 7, v232
	v_mov_b32_e32 v233, v193
	v_lshl_add_u64 v[232:233], v[154:155], 0, v[232:233]
	global_load_dwordx4 v[234:237], v[232:233], off offset:16
	global_load_dwordx4 v[238:241], v[232:233], off
	global_load_dwordx4 v[242:245], v[232:233], off offset:80
	global_load_dwordx4 v[248:251], v[232:233], off offset:64
; __device__ __forceinline__ unsigned cvt_pk_bf16(float lo, float hi) { const cvt_f32x2 v = {lo, hi}; return __builtin_bit_cast(unsigned, __builtin_convertvector(v, cvt_bf16x2)); }
;     __device__ __forceinline__ void operator()(const f32x4 (&acc)[2][2][4][2], const Unit& u, int wr, int wc, int fr, int fq) const {
;     ...
;                 if (do_norm) {
;                     float ss = 0.f;
; #pragma unroll
;                     for (int e = 0; e < 4; ++e) ss += a0[e] * a0[e] + a1[e] * a1[e] + b0[e] * b0[e] + b1[e] * b1[e];
;                     ss += __shfl_xor(ss, 16); ss += __shfl_xor(ss, 32);
;                     const float r = __builtin_amdgcn_rsqf(ss * (1.0f / 64.0f) + 1e-6f);
;                     a0 = a0 * r * ga[0]; a1 = a1 * r * ga[1]; b0 = b0 * r * gb[0]; b1 = b1 * r * gb[1];
;                 }
;                 if (do_rope) {
;                     const int s = row & 4095, pos = half ? (s & 63) : (s >> 6);
;                     const f32x4 c0 = *(const f32x4*)(rope + pos * 32 + jb), c1 = *(const f32x4*)(rope + pos * 32 + jb + 4);
;                     const f32x4 s0 = *(const f32x4*)(rope + pos * 32 + 16 + jb), s1 = *(const f32x4*)(rope + pos * 32 + 16 + jb + 4);
;                     const f32x4 x0 = a0, x1 = a1, y0 = b0, y1 = b1;
;                     a0 = x0 * c0 - y0 * s0; b0 = y0 * c0 + x0 * s0; a1 = x1 * c1 - y1 * s1; b1 = y1 * c1 + x1 * s1;
;                 }
;                 a0 = a0 * qs; a1 = a1 * qs; b0 = b0 * qs; b1 = b1 * qs;
;                 bf16_t* rowp = O + (size_t)row * ldc + hs * 64 + D0;
;                 u32x4 w;
;                 w.x = cvt_pk_bf16(a0[0], a0[1]); w.y = cvt_pk_bf16(a0[2], a0[3]); w.z = cvt_pk_bf16(a1[0], a1[1]); w.w = cvt_pk_bf16(a1[2], a1[3]); *(u32x4*)(rowp) = w;
;                 w.x = cvt_pk_bf16(b0[0], b0[1]); w.y = cvt_pk_bf16(b0[2], b0[3]); w.z = cvt_pk_bf16(b1[0], b1[1]); w.w = cvt_pk_bf16(b1[2], b1[3]); *(u32x4*)(rowp + 16) = w;
.LBB0_65:
	v_or_b32_e32 v116, s3, v164
	v_pk_mul_f32 v[114:115], v[160:161], v[96:97]
	v_mad_i64_i32 v[96:97], s[4:5], v116, s38, 0
	v_mov_b32_e32 v112, v160
	v_mov_b32_e32 v113, v160
	v_lshl_add_u64 v[96:97], v[96:97], 1, s[58:59]
	v_pk_mul_f32 v[110:111], v[112:113], v[110:111]
	v_pk_mul_f32 v[108:109], v[160:161], v[108:109]
	v_pk_mul_f32 v[106:107], v[112:113], v[106:107]
	v_pk_mul_f32 v[104:105], v[160:161], v[104:105]
	v_lshl_add_u64 v[96:97], s[14:15], 1, v[96:97]
	v_pk_mul_f32 v[102:103], v[112:113], v[102:103]
	v_pk_mul_f32 v[100:101], v[160:161], v[100:101]
	v_pk_mul_f32 v[112:113], v[112:113], v[98:99]
	v_lshl_add_u64 v[116:117], v[96:97], 0, v[192:193]
	v_cvt_pk_bf16_f32 v96, v108, v109
	v_cvt_pk_bf16_f32 v97, v110, v111
	v_cvt_pk_bf16_f32 v98, v104, v105
	v_cvt_pk_bf16_f32 v99, v106, v107
	global_store_dwordx4 v[116:117], v[96:99], off
	s_and_b64 vcc, exec, s[10:11]
	s_nop 0
	v_cvt_pk_bf16_f32 v96, v100, v101
	v_cvt_pk_bf16_f32 v97, v102, v103
	v_cvt_pk_bf16_f32 v98, v114, v115
	v_cvt_pk_bf16_f32 v99, v112, v113
	global_store_dwordx4 v[116:117], v[96:99], off offset:32
	s_cbranch_vccnz .LBB0_67
	s_nop 0
	v_pk_mul_f32 v[98:99], v[88:89], v[88:89]
	v_pk_mul_f32 v[96:97], v[90:91], v[90:91]
	v_pk_fma_f32 v[98:99], v[92:93], v[92:93], v[98:99]
	v_pk_fma_f32 v[96:97], v[94:95], v[94:95], v[96:97]
	v_pk_fma_f32 v[98:99], v[84:85], v[84:85], v[98:99]
	v_pk_fma_f32 v[96:97], v[86:87], v[86:87], v[96:97]
	v_pk_fma_f32 v[98:99], v[80:81], v[80:81], v[98:99]
	v_pk_fma_f32 v[96:97], v[82:83], v[82:83], v[96:97]
	v_add_f32_e32 v98, v98, v99
	v_add_f32_e32 v96, v96, v98
	v_add_f32_e32 v96, v97, v96
	ds_bpermute_b32 v97, v166, v96
	s_waitcnt lgkmcnt(0)
	v_add_f32_e32 v96, v96, v97
	ds_bpermute_b32 v97, v167, v96
	s_waitcnt lgkmcnt(0)
	v_add_f32_e32 v96, v96, v97
	v_fmamk_f32 v96, v96, 0x3c800000, v224
	v_rsq_f32_e32 v96, v96
	s_nop 0
	v_pk_mul_f32 v[92:93], v[92:93], v[96:97] op_sel_hi:[1,0]
	v_pk_mul_f32 v[94:95], v[94:95], v[96:97] op_sel_hi:[1,0]
	v_pk_mul_f32 v[88:89], v[88:89], v[96:97] op_sel_hi:[1,0]
	v_pk_mul_f32 v[90:91], v[90:91], v[96:97] op_sel_hi:[1,0]
	v_pk_mul_f32 v[84:85], v[84:85], v[96:97] op_sel_hi:[1,0]
	v_pk_mul_f32 v[86:87], v[86:87], v[96:97] op_sel_hi:[1,0]
	v_pk_mul_f32 v[80:81], v[80:81], v[96:97] op_sel_hi:[1,0]
	v_pk_mul_f32 v[82:83], v[82:83], v[96:97] op_sel_hi:[1,0]
	v_pk_mul_f32 v[94:95], v[70:71], v[94:95]
	v_pk_mul_f32 v[92:93], v[68:69], v[92:93]
	v_pk_mul_f32 v[90:91], v[78:79], v[90:91]
	v_pk_mul_f32 v[88:89], v[76:77], v[88:89]
	v_pk_mul_f32 v[86:87], v[58:59], v[86:87]
	v_pk_mul_f32 v[84:85], v[56:57], v[84:85]
	v_pk_mul_f32 v[82:83], v[66:67], v[82:83]
	v_pk_mul_f32 v[80:81], v[64:65], v[80:81]
.LBB0_67:
	s_and_b64 vcc, exec, s[12:13]
	s_cbranch_vccnz .LBB0_69
	s_waitcnt vmcnt(2)
	v_pk_mul_f32 v[112:113], v[86:87], v[250:251]
	v_pk_mul_f32 v[116:117], v[84:85], v[248:249]
	v_pk_fma_f32 v[114:115], v[94:95], v[240:241], v[112:113] neg_lo:[0,0,1] neg_hi:[0,0,1]
	v_pk_fma_f32 v[112:113], v[92:93], v[238:239], v[116:117] neg_lo:[0,0,1] neg_hi:[0,0,1]
	v_pk_mul_f32 v[92:93], v[92:93], v[248:249]
	v_pk_mul_f32 v[94:95], v[94:95], v[250:251]
	v_pk_fma_f32 v[84:85], v[84:85], v[238:239], v[92:93]
	v_pk_mul_f32 v[92:93], v[82:83], v[244:245]
	v_pk_mul_f32 v[238:239], v[80:81], v[242:243]
	v_pk_fma_f32 v[86:87], v[86:87], v[240:241], v[94:95]
	v_pk_fma_f32 v[94:95], v[90:91], v[236:237], v[92:93] neg_lo:[0,0,1] neg_hi:[0,0,1]
	v_pk_fma_f32 v[92:93], v[88:89], v[234:235], v[238:239] neg_lo:[0,0,1] neg_hi:[0,0,1]
	v_pk_mul_f32 v[90:91], v[90:91], v[244:245]
	v_pk_mul_f32 v[88:89], v[88:89], v[242:243]
	v_pk_fma_f32 v[82:83], v[82:83], v[236:237], v[90:91]
	v_pk_fma_f32 v[80:81], v[80:81], v[234:235], v[88:89]
	v_mov_b64_e32 v[88:89], v[92:93]
	v_mov_b64_e32 v[90:91], v[94:95]
	v_mov_b64_e32 v[92:93], v[112:113]
	v_mov_b64_e32 v[94:95], v[114:115]
	s_add_i32 s23, s3, 0x80
	s_bfe_u32 s23, s23, 0x60006
	v_mov_b32_e32 v232, s23
	v_cndmask_b32_e64 v232, v153, v232, s[6:7]
	v_lshlrev_b32_e32 v232, 7, v232
	v_mov_b32_e32 v233, v193
	v_lshl_add_u64 v[232:233], v[154:155], 0, v[232:233]
	global_load_dwordx4 v[200:203], v[232:233], off offset:16
	global_load_dwordx4 v[204:207], v[232:233], off
	global_load_dwordx4 v[208:211], v[232:233], off offset:80
	global_load_dwordx4 v[212:215], v[232:233], off offset:64
.LBB0_69:
	v_or_b32_e32 v100, s3, v165
	v_pk_mul_f32 v[98:99], v[160:161], v[80:81]
	v_mad_i64_i32 v[80:81], s[4:5], v100, s38, 0
	v_mov_b32_e32 v96, v160
	v_mov_b32_e32 v97, v160
	v_lshl_add_u64 v[80:81], v[80:81], 1, s[58:59]
	v_pk_mul_f32 v[94:95], v[96:97], v[94:95]
	v_pk_mul_f32 v[92:93], v[160:161], v[92:93]
	v_pk_mul_f32 v[90:91], v[96:97], v[90:91]
	v_pk_mul_f32 v[88:89], v[160:161], v[88:89]
	v_lshl_add_u64 v[80:81], s[14:15], 1, v[80:81]
	v_pk_mul_f32 v[86:87], v[96:97], v[86:87]
	v_pk_mul_f32 v[84:85], v[160:161], v[84:85]
	v_pk_mul_f32 v[96:97], v[96:97], v[82:83]
	v_lshl_add_u64 v[100:101], v[80:81], 0, v[192:193]
	v_cvt_pk_bf16_f32 v80, v92, v93
	v_cvt_pk_bf16_f32 v81, v94, v95
	v_cvt_pk_bf16_f32 v82, v88, v89
	v_cvt_pk_bf16_f32 v83, v90, v91
	global_store_dwordx4 v[100:101], v[80:83], off
	s_and_b64 vcc, exec, s[10:11]
	s_nop 0
	v_cvt_pk_bf16_f32 v80, v84, v85
	v_cvt_pk_bf16_f32 v81, v86, v87
	v_cvt_pk_bf16_f32 v82, v98, v99
	v_cvt_pk_bf16_f32 v83, v96, v97
	global_store_dwordx4 v[100:101], v[80:83], off offset:32
	s_cbranch_vccnz .LBB0_71
	s_nop 0
	v_pk_mul_f32 v[82:83], v[60:61], v[60:61]
	v_pk_mul_f32 v[80:81], v[62:63], v[62:63]
	v_pk_fma_f32 v[82:83], v[72:73], v[72:73], v[82:83]
	v_pk_fma_f32 v[80:81], v[74:75], v[74:75], v[80:81]
	v_pk_fma_f32 v[82:83], v[52:53], v[52:53], v[82:83]
	v_pk_fma_f32 v[80:81], v[54:55], v[54:55], v[80:81]
	v_pk_fma_f32 v[82:83], v[48:49], v[48:49], v[82:83]
	v_pk_fma_f32 v[80:81], v[50:51], v[50:51], v[80:81]
	v_add_f32_e32 v82, v82, v83
	v_add_f32_e32 v80, v80, v82
	v_add_f32_e32 v80, v81, v80
	ds_bpermute_b32 v81, v166, v80
	s_waitcnt lgkmcnt(0)
	v_add_f32_e32 v80, v80, v81
	ds_bpermute_b32 v81, v167, v80
	s_waitcnt lgkmcnt(0)
	v_add_f32_e32 v80, v80, v81
	v_fmamk_f32 v80, v80, 0x3c800000, v224
	v_rsq_f32_e32 v80, v80
	s_nop 0
	v_pk_mul_f32 v[72:73], v[72:73], v[80:81] op_sel_hi:[1,0]
	v_pk_mul_f32 v[74:75], v[74:75], v[80:81] op_sel_hi:[1,0]
	v_pk_mul_f32 v[60:61], v[60:61], v[80:81] op_sel_hi:[1,0]
	v_pk_mul_f32 v[62:63], v[62:63], v[80:81] op_sel_hi:[1,0]
	v_pk_mul_f32 v[52:53], v[52:53], v[80:81] op_sel_hi:[1,0]
	v_pk_mul_f32 v[54:55], v[54:55], v[80:81] op_sel_hi:[1,0]
	v_pk_mul_f32 v[48:49], v[48:49], v[80:81] op_sel_hi:[1,0]
	v_pk_mul_f32 v[50:51], v[50:51], v[80:81] op_sel_hi:[1,0]
	v_pk_mul_f32 v[74:75], v[70:71], v[74:75]
	v_pk_mul_f32 v[72:73], v[68:69], v[72:73]
	v_pk_mul_f32 v[62:63], v[78:79], v[62:63]
	v_pk_mul_f32 v[60:61], v[76:77], v[60:61]
	v_pk_mul_f32 v[54:55], v[58:59], v[54:55]
	v_pk_mul_f32 v[52:53], v[56:57], v[52:53]
	v_pk_mul_f32 v[50:51], v[66:67], v[50:51]
	v_pk_mul_f32 v[48:49], v[64:65], v[48:49]
; __device__ __forceinline__ unsigned cvt_pk_bf16(float lo, float hi) { const cvt_f32x2 v = {lo, hi}; return __builtin_bit_cast(unsigned, __builtin_convertvector(v, cvt_bf16x2)); }
;     __device__ __forceinline__ void operator()(const f32x4 (&acc)[2][2][4][2], const Unit& u, int wr, int wc, int fr, int fq) const {
;     ...
;                 if (do_norm) {
;                     float ss = 0.f;
; #pragma unroll
;                     for (int e = 0; e < 4; ++e) ss += a0[e] * a0[e] + a1[e] * a1[e] + b0[e] * b0[e] + b1[e] * b1[e];
;                     ss += __shfl_xor(ss, 16); ss += __shfl_xor(ss, 32);
;                     const float r = __builtin_amdgcn_rsqf(ss * (1.0f / 64.0f) + 1e-6f);
;                     a0 = a0 * r * ga[0]; a1 = a1 * r * ga[1]; b0 = b0 * r * gb[0]; b1 = b1 * r * gb[1];
;                 }
;                 if (do_rope) {
;                     const int s = row & 4095, pos = half ? (s & 63) : (s >> 6);
;                     const f32x4 c0 = *(const f32x4*)(rope + pos * 32 + jb), c1 = *(const f32x4*)(rope + pos * 32 + jb + 4);
;                     const f32x4 s0 = *(const f32x4*)(rope + pos * 32 + 16 + jb), s1 = *(const f32x4*)(rope + pos * 32 + 16 + jb + 4);
;                     const f32x4 x0 = a0, x1 = a1, y0 = b0, y1 = b1;
;                     a0 = x0 * c0 - y0 * s0; b0 = y0 * c0 + x0 * s0; a1 = x1 * c1 - y1 * s1; b1 = y1 * c1 + x1 * s1;
;                 }
;                 a0 = a0 * qs; a1 = a1 * qs; b0 = b0 * qs; b1 = b1 * qs;
;                 bf16_t* rowp = O + (size_t)row * ldc + hs * 64 + D0;
;                 u32x4 w;
;                 w.x = cvt_pk_bf16(a0[0], a0[1]); w.y = cvt_pk_bf16(a0[2], a0[3]); w.z = cvt_pk_bf16(a1[0], a1[1]); w.w = cvt_pk_bf16(a1[2], a1[3]); *(u32x4*)(rowp) = w;
;                 w.x = cvt_pk_bf16(b0[0], b0[1]); w.y = cvt_pk_bf16(b0[2], b0[3]); w.z = cvt_pk_bf16(b1[0], b1[1]); w.w = cvt_pk_bf16(b1[2], b1[3]); *(u32x4*)(rowp + 16) = w;
.LBB0_71:
	s_addk_i32 s3, 0x80
	s_and_b64 vcc, exec, s[12:13]
	s_bfe_u32 s2, s3, 0x60006
	s_cbranch_vccnz .LBB0_73
	s_waitcnt vmcnt(2)
	v_pk_mul_f32 v[96:97], v[54:55], v[214:215]
	v_pk_mul_f32 v[100:101], v[52:53], v[212:213]
	v_pk_fma_f32 v[98:99], v[74:75], v[206:207], v[96:97] neg_lo:[0,0,1] neg_hi:[0,0,1]
	v_pk_fma_f32 v[96:97], v[72:73], v[204:205], v[100:101] neg_lo:[0,0,1] neg_hi:[0,0,1]
	v_pk_mul_f32 v[72:73], v[72:73], v[212:213]
	v_pk_mul_f32 v[74:75], v[74:75], v[214:215]
	v_pk_fma_f32 v[52:53], v[52:53], v[204:205], v[72:73]
	v_pk_mul_f32 v[72:73], v[50:51], v[210:211]
	v_pk_mul_f32 v[204:205], v[48:49], v[208:209]
	v_pk_fma_f32 v[54:55], v[54:55], v[206:207], v[74:75]
	v_pk_fma_f32 v[74:75], v[62:63], v[202:203], v[72:73] neg_lo:[0,0,1] neg_hi:[0,0,1]
	v_pk_fma_f32 v[72:73], v[60:61], v[200:201], v[204:205] neg_lo:[0,0,1] neg_hi:[0,0,1]
	v_pk_mul_f32 v[62:63], v[62:63], v[210:211]
	v_pk_mul_f32 v[60:61], v[60:61], v[208:209]
	v_pk_fma_f32 v[50:51], v[50:51], v[202:203], v[62:63]
	v_pk_fma_f32 v[48:49], v[48:49], v[200:201], v[60:61]
	v_mov_b64_e32 v[60:61], v[72:73]
	v_mov_b64_e32 v[62:63], v[74:75]
	v_mov_b64_e32 v[72:73], v[96:97]
	v_mov_b64_e32 v[74:75], v[98:99]
	v_mov_b32_e32 v232, s2
	v_cndmask_b32_e64 v232, v163, v232, s[6:7]
	v_lshlrev_b32_e32 v232, 7, v232
	v_mov_b32_e32 v233, v193
	v_lshl_add_u64 v[232:233], v[154:155], 0, v[232:233]
	global_load_dwordx4 v[234:237], v[232:233], off offset:16
	global_load_dwordx4 v[238:241], v[232:233], off
	global_load_dwordx4 v[242:245], v[232:233], off offset:80
	global_load_dwordx4 v[248:251], v[232:233], off offset:64
.LBB0_73:
	v_or_b32_e32 v84, s3, v153
	v_pk_mul_f32 v[82:83], v[160:161], v[48:49]
	v_mad_i64_i32 v[48:49], s[4:5], v84, s38, 0
	v_mov_b32_e32 v80, v160
	v_mov_b32_e32 v81, v160
	v_lshl_add_u64 v[48:49], v[48:49], 1, s[58:59]
	v_pk_mul_f32 v[74:75], v[80:81], v[74:75]
	v_pk_mul_f32 v[72:73], v[160:161], v[72:73]
	v_pk_mul_f32 v[62:63], v[80:81], v[62:63]
	v_pk_mul_f32 v[60:61], v[160:161], v[60:61]
	v_lshl_add_u64 v[48:49], s[14:15], 1, v[48:49]
	v_pk_mul_f32 v[54:55], v[80:81], v[54:55]
	v_pk_mul_f32 v[52:53], v[160:161], v[52:53]
	v_pk_mul_f32 v[80:81], v[80:81], v[50:51]
	v_lshl_add_u64 v[84:85], v[48:49], 0, v[192:193]
	v_cvt_pk_bf16_f32 v48, v72, v73
	v_cvt_pk_bf16_f32 v49, v74, v75
	v_cvt_pk_bf16_f32 v50, v60, v61
	v_cvt_pk_bf16_f32 v51, v62, v63
	global_store_dwordx4 v[84:85], v[48:51], off
	s_and_b64 vcc, exec, s[10:11]
	s_nop 0
	v_cvt_pk_bf16_f32 v48, v52, v53
	v_cvt_pk_bf16_f32 v49, v54, v55
	v_cvt_pk_bf16_f32 v50, v82, v83
	v_cvt_pk_bf16_f32 v51, v80, v81
	global_store_dwordx4 v[84:85], v[48:51], off offset:32
	s_cbranch_vccnz .LBB0_75
	s_nop 0
	v_pk_mul_f32 v[50:51], v[40:41], v[40:41]
	v_pk_mul_f32 v[48:49], v[42:43], v[42:43]
	v_pk_fma_f32 v[50:51], v[44:45], v[44:45], v[50:51]
	v_pk_fma_f32 v[48:49], v[46:47], v[46:47], v[48:49]
	v_pk_fma_f32 v[50:51], v[36:37], v[36:37], v[50:51]
	v_pk_fma_f32 v[48:49], v[38:39], v[38:39], v[48:49]
	v_pk_fma_f32 v[50:51], v[32:33], v[32:33], v[50:51]
	v_pk_fma_f32 v[48:49], v[34:35], v[34:35], v[48:49]
	v_add_f32_e32 v50, v50, v51
	v_add_f32_e32 v48, v48, v50
	v_add_f32_e32 v48, v49, v48
	ds_bpermute_b32 v49, v166, v48
	s_waitcnt lgkmcnt(0)
	v_add_f32_e32 v48, v48, v49
	ds_bpermute_b32 v49, v167, v48
	s_waitcnt lgkmcnt(0)
	v_add_f32_e32 v48, v48, v49
	v_fmamk_f32 v48, v48, 0x3c800000, v224
	v_rsq_f32_e32 v48, v48
	s_nop 0
	v_pk_mul_f32 v[44:45], v[44:45], v[48:49] op_sel_hi:[1,0]
	v_pk_mul_f32 v[46:47], v[46:47], v[48:49] op_sel_hi:[1,0]
	v_pk_mul_f32 v[40:41], v[40:41], v[48:49] op_sel_hi:[1,0]
	v_pk_mul_f32 v[42:43], v[42:43], v[48:49] op_sel_hi:[1,0]
	v_pk_mul_f32 v[36:37], v[36:37], v[48:49] op_sel_hi:[1,0]
	v_pk_mul_f32 v[38:39], v[38:39], v[48:49] op_sel_hi:[1,0]
	v_pk_mul_f32 v[32:33], v[32:33], v[48:49] op_sel_hi:[1,0]
	v_pk_mul_f32 v[34:35], v[34:35], v[48:49] op_sel_hi:[1,0]
	v_pk_mul_f32 v[46:47], v[70:71], v[46:47]
	v_pk_mul_f32 v[44:45], v[68:69], v[44:45]
	v_pk_mul_f32 v[42:43], v[78:79], v[42:43]
	v_pk_mul_f32 v[40:41], v[76:77], v[40:41]
	v_pk_mul_f32 v[38:39], v[58:59], v[38:39]
	v_pk_mul_f32 v[36:37], v[56:57], v[36:37]
	v_pk_mul_f32 v[34:35], v[66:67], v[34:35]
	v_pk_mul_f32 v[32:33], v[64:65], v[32:33]
.LBB0_75:
	s_and_b64 vcc, exec, s[12:13]
	s_cbranch_vccnz .LBB0_77
	s_waitcnt vmcnt(2)
	v_pk_mul_f32 v[80:81], v[38:39], v[250:251]
	v_pk_mul_f32 v[84:85], v[36:37], v[248:249]
	v_pk_fma_f32 v[82:83], v[46:47], v[240:241], v[80:81] neg_lo:[0,0,1] neg_hi:[0,0,1]
	v_pk_fma_f32 v[80:81], v[44:45], v[238:239], v[84:85] neg_lo:[0,0,1] neg_hi:[0,0,1]
	v_pk_mul_f32 v[44:45], v[44:45], v[248:249]
	v_pk_mul_f32 v[46:47], v[46:47], v[250:251]
	v_pk_fma_f32 v[36:37], v[36:37], v[238:239], v[44:45]
	v_pk_mul_f32 v[44:45], v[34:35], v[244:245]
	v_pk_mul_f32 v[238:239], v[32:33], v[242:243]
	v_pk_fma_f32 v[38:39], v[38:39], v[240:241], v[46:47]
	v_pk_fma_f32 v[46:47], v[42:43], v[236:237], v[44:45] neg_lo:[0,0,1] neg_hi:[0,0,1]
	v_pk_fma_f32 v[44:45], v[40:41], v[234:235], v[238:239] neg_lo:[0,0,1] neg_hi:[0,0,1]
	v_pk_mul_f32 v[42:43], v[42:43], v[244:245]
	v_pk_mul_f32 v[40:41], v[40:41], v[242:243]
	v_pk_fma_f32 v[34:35], v[34:35], v[236:237], v[42:43]
	v_pk_fma_f32 v[32:33], v[32:33], v[234:235], v[40:41]
	v_mov_b64_e32 v[40:41], v[44:45]
	v_mov_b64_e32 v[42:43], v[46:47]
	v_mov_b64_e32 v[44:45], v[80:81]
	v_mov_b64_e32 v[46:47], v[82:83]
	v_mov_b32_e32 v232, s2
	v_cndmask_b32_e64 v232, v164, v232, s[6:7]
	v_lshlrev_b32_e32 v232, 7, v232
	v_mov_b32_e32 v233, v193
	v_lshl_add_u64 v[232:233], v[154:155], 0, v[232:233]
	global_load_dwordx4 v[200:203], v[232:233], off offset:16
	global_load_dwordx4 v[204:207], v[232:233], off
	global_load_dwordx4 v[208:211], v[232:233], off offset:80
	global_load_dwordx4 v[212:215], v[232:233], off offset:64
; __device__ __forceinline__ unsigned cvt_pk_bf16(float lo, float hi) { const cvt_f32x2 v = {lo, hi}; return __builtin_bit_cast(unsigned, __builtin_convertvector(v, cvt_bf16x2)); }
;     __device__ __forceinline__ void operator()(const f32x4 (&acc)[2][2][4][2], const Unit& u, int wr, int wc, int fr, int fq) const {
;     ...
;                 if (do_norm) {
;                     float ss = 0.f;
; #pragma unroll
;                     for (int e = 0; e < 4; ++e) ss += a0[e] * a0[e] + a1[e] * a1[e] + b0[e] * b0[e] + b1[e] * b1[e];
;                     ss += __shfl_xor(ss, 16); ss += __shfl_xor(ss, 32);
;                     const float r = __builtin_amdgcn_rsqf(ss * (1.0f / 64.0f) + 1e-6f);
;                     a0 = a0 * r * ga[0]; a1 = a1 * r * ga[1]; b0 = b0 * r * gb[0]; b1 = b1 * r * gb[1];
;                 }
;                 if (do_rope) {
;                     const int s = row & 4095, pos = half ? (s & 63) : (s >> 6);
;                     const f32x4 c0 = *(const f32x4*)(rope + pos * 32 + jb), c1 = *(const f32x4*)(rope + pos * 32 + jb + 4);
;                     const f32x4 s0 = *(const f32x4*)(rope + pos * 32 + 16 + jb), s1 = *(const f32x4*)(rope + pos * 32 + 16 + jb + 4);
;                     const f32x4 x0 = a0, x1 = a1, y0 = b0, y1 = b1;
;                     a0 = x0 * c0 - y0 * s0; b0 = y0 * c0 + x0 * s0; a1 = x1 * c1 - y1 * s1; b1 = y1 * c1 + x1 * s1;
;                 }
;                 a0 = a0 * qs; a1 = a1 * qs; b0 = b0 * qs; b1 = b1 * qs;
;                 bf16_t* rowp = O + (size_t)row * ldc + hs * 64 + D0;
;                 u32x4 w;
;                 w.x = cvt_pk_bf16(a0[0], a0[1]); w.y = cvt_pk_bf16(a0[2], a0[3]); w.z = cvt_pk_bf16(a1[0], a1[1]); w.w = cvt_pk_bf16(a1[2], a1[3]); *(u32x4*)(rowp) = w;
;                 w.x = cvt_pk_bf16(b0[0], b0[1]); w.y = cvt_pk_bf16(b0[2], b0[3]); w.z = cvt_pk_bf16(b1[0], b1[1]); w.w = cvt_pk_bf16(b1[2], b1[3]); *(u32x4*)(rowp + 16) = w;
.LBB0_77:
	v_or_b32_e32 v52, s3, v163
	v_pk_mul_f32 v[50:51], v[160:161], v[32:33]
	v_mad_i64_i32 v[32:33], s[4:5], v52, s38, 0
	v_mov_b32_e32 v48, v160
	v_mov_b32_e32 v49, v160
	v_lshl_add_u64 v[32:33], v[32:33], 1, s[58:59]
	v_pk_mul_f32 v[46:47], v[48:49], v[46:47]
	v_pk_mul_f32 v[44:45], v[160:161], v[44:45]
	v_pk_mul_f32 v[42:43], v[48:49], v[42:43]
	v_pk_mul_f32 v[40:41], v[160:161], v[40:41]
	v_lshl_add_u64 v[32:33], s[14:15], 1, v[32:33]
	v_pk_mul_f32 v[38:39], v[48:49], v[38:39]
	v_pk_mul_f32 v[36:37], v[160:161], v[36:37]
	v_pk_mul_f32 v[48:49], v[48:49], v[34:35]
	v_lshl_add_u64 v[52:53], v[32:33], 0, v[192:193]
	v_cvt_pk_bf16_f32 v32, v44, v45
	v_cvt_pk_bf16_f32 v33, v46, v47
	v_cvt_pk_bf16_f32 v34, v40, v41
	v_cvt_pk_bf16_f32 v35, v42, v43
	global_store_dwordx4 v[52:53], v[32:35], off
	s_and_b64 vcc, exec, s[10:11]
	s_nop 0
	v_cvt_pk_bf16_f32 v32, v36, v37
	v_cvt_pk_bf16_f32 v33, v38, v39
	v_cvt_pk_bf16_f32 v34, v50, v51
	v_cvt_pk_bf16_f32 v35, v48, v49
	global_store_dwordx4 v[52:53], v[32:35], off offset:32
	s_cbranch_vccnz .LBB0_79
	s_nop 0
	v_pk_mul_f32 v[34:35], v[24:25], v[24:25]
	v_pk_mul_f32 v[32:33], v[26:27], v[26:27]
	v_pk_fma_f32 v[34:35], v[28:29], v[28:29], v[34:35]
	v_pk_fma_f32 v[32:33], v[30:31], v[30:31], v[32:33]
	v_pk_fma_f32 v[34:35], v[20:21], v[20:21], v[34:35]
	v_pk_fma_f32 v[32:33], v[22:23], v[22:23], v[32:33]
	v_pk_fma_f32 v[34:35], v[16:17], v[16:17], v[34:35]
	v_pk_fma_f32 v[32:33], v[18:19], v[18:19], v[32:33]
	v_add_f32_e32 v34, v34, v35
	v_add_f32_e32 v32, v32, v34
	v_add_f32_e32 v32, v33, v32
	ds_bpermute_b32 v33, v166, v32
	s_waitcnt lgkmcnt(0)
	v_add_f32_e32 v32, v32, v33
	ds_bpermute_b32 v33, v167, v32
	s_waitcnt lgkmcnt(0)
	v_add_f32_e32 v32, v32, v33
	v_fmamk_f32 v32, v32, 0x3c800000, v224
	v_rsq_f32_e32 v32, v32
	s_nop 0
	v_pk_mul_f32 v[28:29], v[28:29], v[32:33] op_sel_hi:[1,0]
	v_pk_mul_f32 v[30:31], v[30:31], v[32:33] op_sel_hi:[1,0]
	v_pk_mul_f32 v[24:25], v[24:25], v[32:33] op_sel_hi:[1,0]
	v_pk_mul_f32 v[26:27], v[26:27], v[32:33] op_sel_hi:[1,0]
	v_pk_mul_f32 v[20:21], v[20:21], v[32:33] op_sel_hi:[1,0]
	v_pk_mul_f32 v[22:23], v[22:23], v[32:33] op_sel_hi:[1,0]
	v_pk_mul_f32 v[16:17], v[16:17], v[32:33] op_sel_hi:[1,0]
	v_pk_mul_f32 v[18:19], v[18:19], v[32:33] op_sel_hi:[1,0]
	v_pk_mul_f32 v[30:31], v[70:71], v[30:31]
	v_pk_mul_f32 v[28:29], v[68:69], v[28:29]
	v_pk_mul_f32 v[26:27], v[78:79], v[26:27]
	v_pk_mul_f32 v[24:25], v[76:77], v[24:25]
	v_pk_mul_f32 v[22:23], v[58:59], v[22:23]
	v_pk_mul_f32 v[20:21], v[56:57], v[20:21]
	v_pk_mul_f32 v[18:19], v[66:67], v[18:19]
	v_pk_mul_f32 v[16:17], v[64:65], v[16:17]
.LBB0_79:
	s_and_b64 vcc, exec, s[12:13]
	s_cbranch_vccnz .LBB0_81
	s_waitcnt vmcnt(2)
	v_pk_mul_f32 v[48:49], v[22:23], v[214:215]
	v_pk_mul_f32 v[52:53], v[20:21], v[212:213]
	v_pk_fma_f32 v[50:51], v[30:31], v[206:207], v[48:49] neg_lo:[0,0,1] neg_hi:[0,0,1]
	v_pk_fma_f32 v[48:49], v[28:29], v[204:205], v[52:53] neg_lo:[0,0,1] neg_hi:[0,0,1]
	v_pk_mul_f32 v[28:29], v[28:29], v[212:213]
	v_pk_mul_f32 v[30:31], v[30:31], v[214:215]
	v_pk_fma_f32 v[20:21], v[20:21], v[204:205], v[28:29]
	v_pk_mul_f32 v[28:29], v[18:19], v[210:211]
	v_pk_mul_f32 v[204:205], v[16:17], v[208:209]
	v_pk_fma_f32 v[22:23], v[22:23], v[206:207], v[30:31]
	v_pk_fma_f32 v[30:31], v[26:27], v[202:203], v[28:29] neg_lo:[0,0,1] neg_hi:[0,0,1]
	v_pk_fma_f32 v[28:29], v[24:25], v[200:201], v[204:205] neg_lo:[0,0,1] neg_hi:[0,0,1]
	v_pk_mul_f32 v[26:27], v[26:27], v[210:211]
	v_pk_mul_f32 v[24:25], v[24:25], v[208:209]
	v_pk_fma_f32 v[18:19], v[18:19], v[202:203], v[26:27]
	v_pk_fma_f32 v[16:17], v[16:17], v[200:201], v[24:25]
	v_mov_b64_e32 v[24:25], v[28:29]
	v_mov_b64_e32 v[26:27], v[30:31]
	v_mov_b64_e32 v[28:29], v[48:49]
	v_mov_b64_e32 v[30:31], v[50:51]
	v_mov_b32_e32 v232, s2
	v_cndmask_b32_e64 v232, v165, v232, s[6:7]
	v_lshlrev_b32_e32 v232, 7, v232
	v_mov_b32_e32 v233, v193
	v_lshl_add_u64 v[232:233], v[154:155], 0, v[232:233]
	global_load_dwordx4 v[234:237], v[232:233], off offset:16
	global_load_dwordx4 v[238:241], v[232:233], off
	global_load_dwordx4 v[242:245], v[232:233], off offset:80
	global_load_dwordx4 v[248:251], v[232:233], off offset:64
; __device__ __forceinline__ unsigned cvt_pk_bf16(float lo, float hi) { const cvt_f32x2 v = {lo, hi}; return __builtin_bit_cast(unsigned, __builtin_convertvector(v, cvt_bf16x2)); }
;     __device__ __forceinline__ void operator()(const f32x4 (&acc)[2][2][4][2], const Unit& u, int wr, int wc, int fr, int fq) const {
;     ...
;                 if (do_norm) {
;                     float ss = 0.f;
; #pragma unroll
;                     for (int e = 0; e < 4; ++e) ss += a0[e] * a0[e] + a1[e] * a1[e] + b0[e] * b0[e] + b1[e] * b1[e];
;                     ss += __shfl_xor(ss, 16); ss += __shfl_xor(ss, 32);
;                     const float r = __builtin_amdgcn_rsqf(ss * (1.0f / 64.0f) + 1e-6f);
;                     a0 = a0 * r * ga[0]; a1 = a1 * r * ga[1]; b0 = b0 * r * gb[0]; b1 = b1 * r * gb[1];
;                 }
;                 if (do_rope) {
;                     const int s = row & 4095, pos = half ? (s & 63) : (s >> 6);
;                     const f32x4 c0 = *(const f32x4*)(rope + pos * 32 + jb), c1 = *(const f32x4*)(rope + pos * 32 + jb + 4);
;                     const f32x4 s0 = *(const f32x4*)(rope + pos * 32 + 16 + jb), s1 = *(const f32x4*)(rope + pos * 32 + 16 + jb + 4);
;                     const f32x4 x0 = a0, x1 = a1, y0 = b0, y1 = b1;
;                     a0 = x0 * c0 - y0 * s0; b0 = y0 * c0 + x0 * s0; a1 = x1 * c1 - y1 * s1; b1 = y1 * c1 + x1 * s1;
;                 }
;                 a0 = a0 * qs; a1 = a1 * qs; b0 = b0 * qs; b1 = b1 * qs;
;                 bf16_t* rowp = O + (size_t)row * ldc + hs * 64 + D0;
;                 u32x4 w;
;                 w.x = cvt_pk_bf16(a0[0], a0[1]); w.y = cvt_pk_bf16(a0[2], a0[3]); w.z = cvt_pk_bf16(a1[0], a1[1]); w.w = cvt_pk_bf16(a1[2], a1[3]); *(u32x4*)(rowp) = w;
;                 w.x = cvt_pk_bf16(b0[0], b0[1]); w.y = cvt_pk_bf16(b0[2], b0[3]); w.z = cvt_pk_bf16(b1[0], b1[1]); w.w = cvt_pk_bf16(b1[2], b1[3]); *(u32x4*)(rowp + 16) = w;
.LBB0_81:
	v_or_b32_e32 v36, s3, v164
	v_pk_mul_f32 v[34:35], v[160:161], v[16:17]
	v_mad_i64_i32 v[16:17], s[4:5], v36, s38, 0
	v_mov_b32_e32 v32, v160
	v_mov_b32_e32 v33, v160
	v_lshl_add_u64 v[16:17], v[16:17], 1, s[58:59]
	v_pk_mul_f32 v[30:31], v[32:33], v[30:31]
	v_pk_mul_f32 v[28:29], v[160:161], v[28:29]
	v_pk_mul_f32 v[26:27], v[32:33], v[26:27]
	v_pk_mul_f32 v[24:25], v[160:161], v[24:25]
	v_lshl_add_u64 v[16:17], s[14:15], 1, v[16:17]
	v_pk_mul_f32 v[22:23], v[32:33], v[22:23]
	v_pk_mul_f32 v[20:21], v[160:161], v[20:21]
	v_pk_mul_f32 v[32:33], v[32:33], v[18:19]
	v_lshl_add_u64 v[36:37], v[16:17], 0, v[192:193]
	v_cvt_pk_bf16_f32 v16, v28, v29
	v_cvt_pk_bf16_f32 v17, v30, v31
	v_cvt_pk_bf16_f32 v18, v24, v25
	v_cvt_pk_bf16_f32 v19, v26, v27
	global_store_dwordx4 v[36:37], v[16:19], off
	s_and_b64 vcc, exec, s[10:11]
	s_nop 0
	v_cvt_pk_bf16_f32 v16, v20, v21
	v_cvt_pk_bf16_f32 v17, v22, v23
	v_cvt_pk_bf16_f32 v18, v34, v35
	v_cvt_pk_bf16_f32 v19, v32, v33
	global_store_dwordx4 v[36:37], v[16:19], off offset:32
	s_cbranch_vccnz .LBB0_83
	s_nop 0
	v_pk_mul_f32 v[18:19], v[8:9], v[8:9]
	v_pk_mul_f32 v[16:17], v[10:11], v[10:11]
	v_pk_fma_f32 v[18:19], v[12:13], v[12:13], v[18:19]
	v_pk_fma_f32 v[16:17], v[14:15], v[14:15], v[16:17]
	v_pk_fma_f32 v[18:19], v[4:5], v[4:5], v[18:19]
	v_pk_fma_f32 v[16:17], v[6:7], v[6:7], v[16:17]
	v_pk_fma_f32 v[18:19], v[0:1], v[0:1], v[18:19]
	v_pk_fma_f32 v[16:17], v[2:3], v[2:3], v[16:17]
	v_add_f32_e32 v18, v18, v19
	v_add_f32_e32 v16, v16, v18
	v_add_f32_e32 v16, v17, v16
	ds_bpermute_b32 v17, v166, v16
	s_waitcnt lgkmcnt(0)
	v_add_f32_e32 v16, v16, v17
	ds_bpermute_b32 v17, v167, v16
	s_waitcnt lgkmcnt(0)
	v_add_f32_e32 v16, v16, v17
	v_fmamk_f32 v16, v16, 0x3c800000, v224
	v_rsq_f32_e32 v16, v16
	s_nop 0
	v_pk_mul_f32 v[12:13], v[12:13], v[16:17] op_sel_hi:[1,0]
	v_pk_mul_f32 v[14:15], v[14:15], v[16:17] op_sel_hi:[1,0]
	v_pk_mul_f32 v[8:9], v[8:9], v[16:17] op_sel_hi:[1,0]
	v_pk_mul_f32 v[10:11], v[10:11], v[16:17] op_sel_hi:[1,0]
	v_pk_mul_f32 v[4:5], v[4:5], v[16:17] op_sel_hi:[1,0]
	v_pk_mul_f32 v[6:7], v[6:7], v[16:17] op_sel_hi:[1,0]
	v_pk_mul_f32 v[0:1], v[0:1], v[16:17] op_sel_hi:[1,0]
	v_pk_mul_f32 v[2:3], v[2:3], v[16:17] op_sel_hi:[1,0]
	v_pk_mul_f32 v[14:15], v[70:71], v[14:15]
	v_pk_mul_f32 v[12:13], v[68:69], v[12:13]
	v_pk_mul_f32 v[10:11], v[78:79], v[10:11]
	v_pk_mul_f32 v[8:9], v[76:77], v[8:9]
	v_pk_mul_f32 v[6:7], v[58:59], v[6:7]
	v_pk_mul_f32 v[4:5], v[56:57], v[4:5]
	v_pk_mul_f32 v[2:3], v[66:67], v[2:3]
	v_pk_mul_f32 v[0:1], v[64:65], v[0:1]
.LBB0_83:
	s_and_b64 vcc, exec, s[12:13]
	s_cbranch_vccnz .LBB0_85
	s_waitcnt vmcnt(2)
	v_pk_mul_f32 v[32:33], v[6:7], v[250:251]
	v_pk_mul_f32 v[36:37], v[4:5], v[248:249]
	v_pk_fma_f32 v[34:35], v[14:15], v[240:241], v[32:33] neg_lo:[0,0,1] neg_hi:[0,0,1]
	v_pk_fma_f32 v[32:33], v[12:13], v[238:239], v[36:37] neg_lo:[0,0,1] neg_hi:[0,0,1]
	v_pk_mul_f32 v[12:13], v[12:13], v[248:249]
	v_pk_mul_f32 v[14:15], v[14:15], v[250:251]
	v_pk_fma_f32 v[4:5], v[4:5], v[238:239], v[12:13]
	v_pk_mul_f32 v[12:13], v[2:3], v[244:245]
	v_pk_mul_f32 v[238:239], v[0:1], v[242:243]
	v_pk_fma_f32 v[6:7], v[6:7], v[240:241], v[14:15]
	v_pk_fma_f32 v[14:15], v[10:11], v[236:237], v[12:13] neg_lo:[0,0,1] neg_hi:[0,0,1]
	v_pk_fma_f32 v[12:13], v[8:9], v[234:235], v[238:239] neg_lo:[0,0,1] neg_hi:[0,0,1]
	v_pk_mul_f32 v[10:11], v[10:11], v[244:245]
	v_pk_mul_f32 v[8:9], v[8:9], v[242:243]
	v_pk_fma_f32 v[2:3], v[2:3], v[236:237], v[10:11]
	v_pk_fma_f32 v[0:1], v[0:1], v[234:235], v[8:9]
	v_mov_b64_e32 v[8:9], v[12:13]
	v_mov_b64_e32 v[10:11], v[14:15]
	v_mov_b64_e32 v[12:13], v[32:33]
	v_mov_b64_e32 v[14:15], v[34:35]
